# v18 + accumulator zeroing per unit with 63 v_pk_mov_b32 instead of 127 v_mov_b32 (12 GEMM phases)
# baseline (speedup 1.0000x reference)
; template <class Epi, class Sched, bool ALIGN_EPI = false, bool SP2 = false, bool APERM = false  >
; __device__ __forceinline__ void gemm_phase(PG8_LAS unsigned char* lds, const Gemm g, const Sched& S, const Epi& E, const int wid  ) {
;     ...
;     f32x4 acc[2][2][4][2];
; #pragma unroll
;     for (int a = 0; a < 2; ++a)
; #pragma unroll
;         for (int b = 0; b < 2; ++b)
; #pragma unroll
;             for (int m = 0; m < 4; ++m)
; #pragma unroll
;                 for (int n = 0; n < 2; ++n) acc[a][b][m][n] = (f32x4){0.f, 0.f, 0.f, 0.f};
;     ...
;         for (int a = 0; a < 2; ++a)
; #pragma unroll
;             for (int b = 0; b < 2; ++b)
; #pragma unroll
;                 for (int m = 0; m < 4; ++m)
; #pragma unroll
;                     for (int n = 0; n < 2; ++n) acc[a][b][m][n] = (f32x4){0.f, 0.f, 0.f, 0.f};
.LBB0_80:
	v_mov_b32_e32 v0, 0
	s_mov_b32 s6, s24
	s_mov_b32 s2, s18
	v_mov_b32_e32 v1, v0
	v_pk_mov_b32 v[2:3], v[0:1], v[0:1]
	v_pk_mov_b32 v[4:5], v[0:1], v[0:1]
	v_pk_mov_b32 v[6:7], v[0:1], v[0:1]
	v_pk_mov_b32 v[8:9], v[0:1], v[0:1]
	v_pk_mov_b32 v[10:11], v[0:1], v[0:1]
	v_pk_mov_b32 v[12:13], v[0:1], v[0:1]
	v_pk_mov_b32 v[14:15], v[0:1], v[0:1]
	v_pk_mov_b32 v[16:17], v[0:1], v[0:1]
	v_pk_mov_b32 v[18:19], v[0:1], v[0:1]
	v_pk_mov_b32 v[20:21], v[0:1], v[0:1]
	v_pk_mov_b32 v[22:23], v[0:1], v[0:1]
	v_pk_mov_b32 v[24:25], v[0:1], v[0:1]
	v_pk_mov_b32 v[26:27], v[0:1], v[0:1]
	v_pk_mov_b32 v[28:29], v[0:1], v[0:1]
	v_pk_mov_b32 v[30:31], v[0:1], v[0:1]
	v_pk_mov_b32 v[32:33], v[0:1], v[0:1]
	v_pk_mov_b32 v[34:35], v[0:1], v[0:1]
	v_pk_mov_b32 v[36:37], v[0:1], v[0:1]
	v_pk_mov_b32 v[38:39], v[0:1], v[0:1]
	v_pk_mov_b32 v[40:41], v[0:1], v[0:1]
	v_pk_mov_b32 v[42:43], v[0:1], v[0:1]
	v_pk_mov_b32 v[44:45], v[0:1], v[0:1]
	v_pk_mov_b32 v[46:47], v[0:1], v[0:1]
	v_pk_mov_b32 v[48:49], v[0:1], v[0:1]
	v_pk_mov_b32 v[50:51], v[0:1], v[0:1]
	v_pk_mov_b32 v[52:53], v[0:1], v[0:1]
	v_pk_mov_b32 v[54:55], v[0:1], v[0:1]
	v_pk_mov_b32 v[56:57], v[0:1], v[0:1]
	v_pk_mov_b32 v[58:59], v[0:1], v[0:1]
	v_pk_mov_b32 v[60:61], v[0:1], v[0:1]
	v_pk_mov_b32 v[62:63], v[0:1], v[0:1]
	v_pk_mov_b32 v[64:65], v[0:1], v[0:1]
	v_pk_mov_b32 v[66:67], v[0:1], v[0:1]
	v_pk_mov_b32 v[68:69], v[0:1], v[0:1]
	v_pk_mov_b32 v[70:71], v[0:1], v[0:1]
	v_pk_mov_b32 v[72:73], v[0:1], v[0:1]
	v_pk_mov_b32 v[74:75], v[0:1], v[0:1]
	v_pk_mov_b32 v[76:77], v[0:1], v[0:1]
	v_pk_mov_b32 v[78:79], v[0:1], v[0:1]
	v_pk_mov_b32 v[80:81], v[0:1], v[0:1]
	v_pk_mov_b32 v[82:83], v[0:1], v[0:1]
	v_pk_mov_b32 v[84:85], v[0:1], v[0:1]
	v_pk_mov_b32 v[86:87], v[0:1], v[0:1]
	v_pk_mov_b32 v[88:89], v[0:1], v[0:1]
	v_pk_mov_b32 v[90:91], v[0:1], v[0:1]
	v_pk_mov_b32 v[92:93], v[0:1], v[0:1]
	v_pk_mov_b32 v[94:95], v[0:1], v[0:1]
	v_pk_mov_b32 v[96:97], v[0:1], v[0:1]
	v_pk_mov_b32 v[98:99], v[0:1], v[0:1]
	v_pk_mov_b32 v[100:101], v[0:1], v[0:1]
	v_pk_mov_b32 v[102:103], v[0:1], v[0:1]
	v_pk_mov_b32 v[104:105], v[0:1], v[0:1]
	v_pk_mov_b32 v[106:107], v[0:1], v[0:1]
	v_pk_mov_b32 v[108:109], v[0:1], v[0:1]
	v_pk_mov_b32 v[110:111], v[0:1], v[0:1]
	v_pk_mov_b32 v[112:113], v[0:1], v[0:1]
	v_pk_mov_b32 v[114:115], v[0:1], v[0:1]
	v_pk_mov_b32 v[116:117], v[0:1], v[0:1]
	v_pk_mov_b32 v[118:119], v[0:1], v[0:1]
	v_pk_mov_b32 v[120:121], v[0:1], v[0:1]
	v_pk_mov_b32 v[122:123], v[0:1], v[0:1]
	v_pk_mov_b32 v[124:125], v[0:1], v[0:1]
	v_pk_mov_b32 v[126:127], v[0:1], v[0:1]
	s_mov_b64 s[26:27], s[34:35]
	s_mov_b32 s62, s63
	s_andn2_b64 vcc, exec, s[28:29]
	s_mov_b64 s[86:87], s[30:31]
	s_cbranch_vccz .LBB0_99

; template <class Epi, class Sched, bool ALIGN_EPI = false, bool SP2 = false, bool APERM = false  >
; __device__ __forceinline__ void gemm_phase(PG8_LAS unsigned char* lds, const Gemm g, const Sched& S, const Epi& E, const int wid  ) {
;     ...
;     f32x4 acc[2][2][4][2];
; #pragma unroll
;     for (int a = 0; a < 2; ++a)
; #pragma unroll
;         for (int b = 0; b < 2; ++b)
; #pragma unroll
;             for (int m = 0; m < 4; ++m)
; #pragma unroll
;                 for (int n = 0; n < 2; ++n) acc[a][b][m][n] = (f32x4){0.f, 0.f, 0.f, 0.f};
;     ...
;         for (int a = 0; a < 2; ++a)
; #pragma unroll
;             for (int b = 0; b < 2; ++b)
; #pragma unroll
;                 for (int m = 0; m < 4; ++m)
; #pragma unroll
;                     for (int n = 0; n < 2; ++n) acc[a][b][m][n] = (f32x4){0.f, 0.f, 0.f, 0.f};
.LBB0_288:
	v_mov_b32_e32 v0, 0
	s_mov_b32 s28, s8
	s_mov_b32 s56, s12
	s_mov_b64 s[14:15], s[66:67]
	s_mov_b64 s[0:1], s[26:27]
	s_mov_b32 s74, s75
	v_mov_b32_e32 v1, v0
	v_pk_mov_b32 v[2:3], v[0:1], v[0:1]
	v_pk_mov_b32 v[4:5], v[0:1], v[0:1]
	v_pk_mov_b32 v[6:7], v[0:1], v[0:1]
	v_pk_mov_b32 v[8:9], v[0:1], v[0:1]
	v_pk_mov_b32 v[10:11], v[0:1], v[0:1]
	v_pk_mov_b32 v[12:13], v[0:1], v[0:1]
	v_pk_mov_b32 v[14:15], v[0:1], v[0:1]
	v_pk_mov_b32 v[16:17], v[0:1], v[0:1]
	v_pk_mov_b32 v[18:19], v[0:1], v[0:1]
	v_pk_mov_b32 v[20:21], v[0:1], v[0:1]
	v_pk_mov_b32 v[22:23], v[0:1], v[0:1]
	v_pk_mov_b32 v[24:25], v[0:1], v[0:1]
	v_pk_mov_b32 v[26:27], v[0:1], v[0:1]
	v_pk_mov_b32 v[28:29], v[0:1], v[0:1]
	v_pk_mov_b32 v[30:31], v[0:1], v[0:1]
	v_pk_mov_b32 v[32:33], v[0:1], v[0:1]
	v_pk_mov_b32 v[34:35], v[0:1], v[0:1]
	v_pk_mov_b32 v[36:37], v[0:1], v[0:1]
	v_pk_mov_b32 v[38:39], v[0:1], v[0:1]
	v_pk_mov_b32 v[40:41], v[0:1], v[0:1]
	v_pk_mov_b32 v[42:43], v[0:1], v[0:1]
	v_pk_mov_b32 v[44:45], v[0:1], v[0:1]
	v_pk_mov_b32 v[46:47], v[0:1], v[0:1]
	v_pk_mov_b32 v[48:49], v[0:1], v[0:1]
	v_pk_mov_b32 v[50:51], v[0:1], v[0:1]
	v_pk_mov_b32 v[52:53], v[0:1], v[0:1]
	v_pk_mov_b32 v[54:55], v[0:1], v[0:1]
	v_pk_mov_b32 v[56:57], v[0:1], v[0:1]
	v_pk_mov_b32 v[58:59], v[0:1], v[0:1]
	v_pk_mov_b32 v[60:61], v[0:1], v[0:1]
	v_pk_mov_b32 v[62:63], v[0:1], v[0:1]
	v_pk_mov_b32 v[64:65], v[0:1], v[0:1]
	v_pk_mov_b32 v[66:67], v[0:1], v[0:1]
	v_pk_mov_b32 v[68:69], v[0:1], v[0:1]
	v_pk_mov_b32 v[70:71], v[0:1], v[0:1]
	v_pk_mov_b32 v[72:73], v[0:1], v[0:1]
	v_pk_mov_b32 v[74:75], v[0:1], v[0:1]
	v_pk_mov_b32 v[76:77], v[0:1], v[0:1]
	v_pk_mov_b32 v[78:79], v[0:1], v[0:1]
	v_pk_mov_b32 v[80:81], v[0:1], v[0:1]
	v_pk_mov_b32 v[82:83], v[0:1], v[0:1]
	v_pk_mov_b32 v[84:85], v[0:1], v[0:1]
	v_pk_mov_b32 v[86:87], v[0:1], v[0:1]
	v_pk_mov_b32 v[88:89], v[0:1], v[0:1]
	v_pk_mov_b32 v[90:91], v[0:1], v[0:1]
	v_pk_mov_b32 v[92:93], v[0:1], v[0:1]
	v_pk_mov_b32 v[94:95], v[0:1], v[0:1]
	v_pk_mov_b32 v[96:97], v[0:1], v[0:1]
	v_pk_mov_b32 v[98:99], v[0:1], v[0:1]
	v_pk_mov_b32 v[100:101], v[0:1], v[0:1]
	v_pk_mov_b32 v[102:103], v[0:1], v[0:1]
	v_pk_mov_b32 v[104:105], v[0:1], v[0:1]
	v_pk_mov_b32 v[106:107], v[0:1], v[0:1]
	v_pk_mov_b32 v[108:109], v[0:1], v[0:1]
	v_pk_mov_b32 v[110:111], v[0:1], v[0:1]
	v_pk_mov_b32 v[112:113], v[0:1], v[0:1]
	v_pk_mov_b32 v[114:115], v[0:1], v[0:1]
	v_pk_mov_b32 v[116:117], v[0:1], v[0:1]
	v_pk_mov_b32 v[118:119], v[0:1], v[0:1]
	v_pk_mov_b32 v[120:121], v[0:1], v[0:1]
	v_pk_mov_b32 v[122:123], v[0:1], v[0:1]
	v_pk_mov_b32 v[124:125], v[0:1], v[0:1]
	v_pk_mov_b32 v[126:127], v[0:1], v[0:1]

; template <class Epi, class Sched, bool ALIGN_EPI = false, bool SP2 = false, bool APERM = false  >
; __device__ __forceinline__ void gemm_phase(PG8_LAS unsigned char* lds, const Gemm g, const Sched& S, const Epi& E, const int wid  ) {
;     ...
;     f32x4 acc[2][2][4][2];
; #pragma unroll
;     for (int a = 0; a < 2; ++a)
; #pragma unroll
;         for (int b = 0; b < 2; ++b)
; #pragma unroll
;             for (int m = 0; m < 4; ++m)
; #pragma unroll
;                 for (int n = 0; n < 2; ++n) acc[a][b][m][n] = (f32x4){0.f, 0.f, 0.f, 0.f};
;     ...
;         for (int a = 0; a < 2; ++a)
; #pragma unroll
;             for (int b = 0; b < 2; ++b)
; #pragma unroll
;                 for (int m = 0; m < 4; ++m)
; #pragma unroll
;                     for (int n = 0; n < 2; ++n) acc[a][b][m][n] = (f32x4){0.f, 0.f, 0.f, 0.f};
.LBB0_463:
	v_mov_b32_e32 v0, 0
	s_mov_b32 s4, s54
	s_mov_b32 s0, s34
	s_mov_b64 s[56:57], s[28:29]
	s_mov_b64 s[60:61], s[24:25]
	s_mov_b32 s77, s78
	v_mov_b32_e32 v1, v0
	v_pk_mov_b32 v[2:3], v[0:1], v[0:1]
	v_pk_mov_b32 v[4:5], v[0:1], v[0:1]
	v_pk_mov_b32 v[6:7], v[0:1], v[0:1]
	v_pk_mov_b32 v[8:9], v[0:1], v[0:1]
	v_pk_mov_b32 v[10:11], v[0:1], v[0:1]
	v_pk_mov_b32 v[12:13], v[0:1], v[0:1]
	v_pk_mov_b32 v[14:15], v[0:1], v[0:1]
	v_pk_mov_b32 v[16:17], v[0:1], v[0:1]
	v_pk_mov_b32 v[18:19], v[0:1], v[0:1]
	v_pk_mov_b32 v[20:21], v[0:1], v[0:1]
	v_pk_mov_b32 v[22:23], v[0:1], v[0:1]
	v_pk_mov_b32 v[24:25], v[0:1], v[0:1]
	v_pk_mov_b32 v[26:27], v[0:1], v[0:1]
	v_pk_mov_b32 v[28:29], v[0:1], v[0:1]
	v_pk_mov_b32 v[30:31], v[0:1], v[0:1]
	v_pk_mov_b32 v[32:33], v[0:1], v[0:1]
	v_pk_mov_b32 v[34:35], v[0:1], v[0:1]
	v_pk_mov_b32 v[36:37], v[0:1], v[0:1]
	v_pk_mov_b32 v[38:39], v[0:1], v[0:1]
	v_pk_mov_b32 v[40:41], v[0:1], v[0:1]
	v_pk_mov_b32 v[42:43], v[0:1], v[0:1]
	v_pk_mov_b32 v[44:45], v[0:1], v[0:1]
	v_pk_mov_b32 v[46:47], v[0:1], v[0:1]
	v_pk_mov_b32 v[48:49], v[0:1], v[0:1]
	v_pk_mov_b32 v[50:51], v[0:1], v[0:1]
	v_pk_mov_b32 v[52:53], v[0:1], v[0:1]
	v_pk_mov_b32 v[54:55], v[0:1], v[0:1]
	v_pk_mov_b32 v[56:57], v[0:1], v[0:1]
	v_pk_mov_b32 v[58:59], v[0:1], v[0:1]
	v_pk_mov_b32 v[60:61], v[0:1], v[0:1]
	v_pk_mov_b32 v[62:63], v[0:1], v[0:1]
	v_pk_mov_b32 v[64:65], v[0:1], v[0:1]
	v_pk_mov_b32 v[66:67], v[0:1], v[0:1]
	v_pk_mov_b32 v[68:69], v[0:1], v[0:1]
	v_pk_mov_b32 v[70:71], v[0:1], v[0:1]
	v_pk_mov_b32 v[72:73], v[0:1], v[0:1]
	v_pk_mov_b32 v[74:75], v[0:1], v[0:1]
	v_pk_mov_b32 v[76:77], v[0:1], v[0:1]
	v_pk_mov_b32 v[78:79], v[0:1], v[0:1]
	v_pk_mov_b32 v[80:81], v[0:1], v[0:1]
	v_pk_mov_b32 v[82:83], v[0:1], v[0:1]
	v_pk_mov_b32 v[84:85], v[0:1], v[0:1]
	v_pk_mov_b32 v[86:87], v[0:1], v[0:1]
	v_pk_mov_b32 v[88:89], v[0:1], v[0:1]
	v_pk_mov_b32 v[90:91], v[0:1], v[0:1]
	v_pk_mov_b32 v[92:93], v[0:1], v[0:1]
	v_pk_mov_b32 v[94:95], v[0:1], v[0:1]
	v_pk_mov_b32 v[96:97], v[0:1], v[0:1]
	v_pk_mov_b32 v[98:99], v[0:1], v[0:1]
	v_pk_mov_b32 v[100:101], v[0:1], v[0:1]
	v_pk_mov_b32 v[102:103], v[0:1], v[0:1]
	v_pk_mov_b32 v[104:105], v[0:1], v[0:1]
	v_pk_mov_b32 v[106:107], v[0:1], v[0:1]
	v_pk_mov_b32 v[108:109], v[0:1], v[0:1]
	v_pk_mov_b32 v[110:111], v[0:1], v[0:1]
	v_pk_mov_b32 v[112:113], v[0:1], v[0:1]
	v_pk_mov_b32 v[114:115], v[0:1], v[0:1]
	v_pk_mov_b32 v[116:117], v[0:1], v[0:1]
	v_pk_mov_b32 v[118:119], v[0:1], v[0:1]
	v_pk_mov_b32 v[120:121], v[0:1], v[0:1]
	v_pk_mov_b32 v[122:123], v[0:1], v[0:1]
	v_pk_mov_b32 v[124:125], v[0:1], v[0:1]
	v_pk_mov_b32 v[126:127], v[0:1], v[0:1]

; template <class Epi, class Sched, bool ALIGN_EPI = false, bool SP2 = false, bool APERM = false  >
; __device__ __forceinline__ void gemm_phase(PG8_LAS unsigned char* lds, const Gemm g, const Sched& S, const Epi& E, const int wid  ) {
;     ...
;     f32x4 acc[2][2][4][2];
; #pragma unroll
;     for (int a = 0; a < 2; ++a)
; #pragma unroll
;         for (int b = 0; b < 2; ++b)
; #pragma unroll
;             for (int m = 0; m < 4; ++m)
; #pragma unroll
;                 for (int n = 0; n < 2; ++n) acc[a][b][m][n] = (f32x4){0.f, 0.f, 0.f, 0.f};
;     ...
;         for (int a = 0; a < 2; ++a)
; #pragma unroll
;             for (int b = 0; b < 2; ++b)
; #pragma unroll
;                 for (int m = 0; m < 4; ++m)
; #pragma unroll
;                     for (int n = 0; n < 2; ++n) acc[a][b][m][n] = (f32x4){0.f, 0.f, 0.f, 0.f};
.LBB0_517:
	v_mov_b32_e32 v0, 0
	s_mov_b32 s81, s65
	s_mov_b32 s68, s82
	s_mov_b64 s[12:13], s[90:91]
	s_mov_b64 s[0:1], s[88:89]
	s_mov_b32 s83, s69
	v_mov_b32_e32 v1, v0
	v_pk_mov_b32 v[2:3], v[0:1], v[0:1]
	v_pk_mov_b32 v[4:5], v[0:1], v[0:1]
	v_pk_mov_b32 v[6:7], v[0:1], v[0:1]
	v_pk_mov_b32 v[8:9], v[0:1], v[0:1]
	v_pk_mov_b32 v[10:11], v[0:1], v[0:1]
	v_pk_mov_b32 v[12:13], v[0:1], v[0:1]
	v_pk_mov_b32 v[14:15], v[0:1], v[0:1]
	v_pk_mov_b32 v[16:17], v[0:1], v[0:1]
	v_pk_mov_b32 v[18:19], v[0:1], v[0:1]
	v_pk_mov_b32 v[20:21], v[0:1], v[0:1]
	v_pk_mov_b32 v[22:23], v[0:1], v[0:1]
	v_pk_mov_b32 v[24:25], v[0:1], v[0:1]
	v_pk_mov_b32 v[26:27], v[0:1], v[0:1]
	v_pk_mov_b32 v[28:29], v[0:1], v[0:1]
	v_pk_mov_b32 v[30:31], v[0:1], v[0:1]
	v_pk_mov_b32 v[32:33], v[0:1], v[0:1]
	v_pk_mov_b32 v[34:35], v[0:1], v[0:1]
	v_pk_mov_b32 v[36:37], v[0:1], v[0:1]
	v_pk_mov_b32 v[38:39], v[0:1], v[0:1]
	v_pk_mov_b32 v[40:41], v[0:1], v[0:1]
	v_pk_mov_b32 v[42:43], v[0:1], v[0:1]
	v_pk_mov_b32 v[44:45], v[0:1], v[0:1]
	v_pk_mov_b32 v[46:47], v[0:1], v[0:1]
	v_pk_mov_b32 v[48:49], v[0:1], v[0:1]
	v_pk_mov_b32 v[50:51], v[0:1], v[0:1]
	v_pk_mov_b32 v[52:53], v[0:1], v[0:1]
	v_pk_mov_b32 v[54:55], v[0:1], v[0:1]
	v_pk_mov_b32 v[56:57], v[0:1], v[0:1]
	v_pk_mov_b32 v[58:59], v[0:1], v[0:1]
	v_pk_mov_b32 v[60:61], v[0:1], v[0:1]
	v_pk_mov_b32 v[62:63], v[0:1], v[0:1]
	v_pk_mov_b32 v[64:65], v[0:1], v[0:1]
	v_pk_mov_b32 v[66:67], v[0:1], v[0:1]
	v_pk_mov_b32 v[68:69], v[0:1], v[0:1]
	v_pk_mov_b32 v[70:71], v[0:1], v[0:1]
	v_pk_mov_b32 v[72:73], v[0:1], v[0:1]
	v_pk_mov_b32 v[74:75], v[0:1], v[0:1]
	v_pk_mov_b32 v[76:77], v[0:1], v[0:1]
	v_pk_mov_b32 v[78:79], v[0:1], v[0:1]
	v_pk_mov_b32 v[80:81], v[0:1], v[0:1]
	v_pk_mov_b32 v[82:83], v[0:1], v[0:1]
	v_pk_mov_b32 v[84:85], v[0:1], v[0:1]
	v_pk_mov_b32 v[86:87], v[0:1], v[0:1]
	v_pk_mov_b32 v[88:89], v[0:1], v[0:1]
	v_pk_mov_b32 v[90:91], v[0:1], v[0:1]
	v_pk_mov_b32 v[92:93], v[0:1], v[0:1]
	v_pk_mov_b32 v[94:95], v[0:1], v[0:1]
	v_pk_mov_b32 v[96:97], v[0:1], v[0:1]
	v_pk_mov_b32 v[98:99], v[0:1], v[0:1]
	v_pk_mov_b32 v[100:101], v[0:1], v[0:1]
	v_pk_mov_b32 v[102:103], v[0:1], v[0:1]
	v_pk_mov_b32 v[104:105], v[0:1], v[0:1]
	v_pk_mov_b32 v[106:107], v[0:1], v[0:1]
	v_pk_mov_b32 v[108:109], v[0:1], v[0:1]
	v_pk_mov_b32 v[110:111], v[0:1], v[0:1]
	v_pk_mov_b32 v[112:113], v[0:1], v[0:1]
	v_pk_mov_b32 v[114:115], v[0:1], v[0:1]
	v_pk_mov_b32 v[116:117], v[0:1], v[0:1]
	v_pk_mov_b32 v[118:119], v[0:1], v[0:1]
	v_pk_mov_b32 v[120:121], v[0:1], v[0:1]
	v_pk_mov_b32 v[122:123], v[0:1], v[0:1]
	v_pk_mov_b32 v[124:125], v[0:1], v[0:1]
	v_pk_mov_b32 v[126:127], v[0:1], v[0:1]

; template <class Epi, class Sched, bool ALIGN_EPI = false, bool SP2 = false, bool APERM = false  >
; __device__ __forceinline__ void gemm_phase(PG8_LAS unsigned char* lds, const Gemm g, const Sched& S, const Epi& E, const int wid  ) {
;     ...
;     f32x4 acc[2][2][4][2];
; #pragma unroll
;     for (int a = 0; a < 2; ++a)
; #pragma unroll
;         for (int b = 0; b < 2; ++b)
; #pragma unroll
;             for (int m = 0; m < 4; ++m)
; #pragma unroll
;                 for (int n = 0; n < 2; ++n) acc[a][b][m][n] = (f32x4){0.f, 0.f, 0.f, 0.f};
;     ...
;         for (int a = 0; a < 2; ++a)
; #pragma unroll
;             for (int b = 0; b < 2; ++b)
; #pragma unroll
;                 for (int m = 0; m < 4; ++m)
; #pragma unroll
;                     for (int n = 0; n < 2; ++n) acc[a][b][m][n] = (f32x4){0.f, 0.f, 0.f, 0.f};
.LBB0_579:
	v_mov_b32_e32 v0, 0
	s_mov_b32 s90, s66
	s_mov_b32 s67, s91
	s_mov_b64 s[12:13], s[28:29]
	s_mov_b64 s[0:1], s[24:25]
	s_mov_b32 s92, s74
	v_mov_b32_e32 v1, v0
	v_pk_mov_b32 v[2:3], v[0:1], v[0:1]
	v_pk_mov_b32 v[4:5], v[0:1], v[0:1]
	v_pk_mov_b32 v[6:7], v[0:1], v[0:1]
	v_pk_mov_b32 v[8:9], v[0:1], v[0:1]
	v_pk_mov_b32 v[10:11], v[0:1], v[0:1]
	v_pk_mov_b32 v[12:13], v[0:1], v[0:1]
	v_pk_mov_b32 v[14:15], v[0:1], v[0:1]
	v_pk_mov_b32 v[16:17], v[0:1], v[0:1]
	v_pk_mov_b32 v[18:19], v[0:1], v[0:1]
	v_pk_mov_b32 v[20:21], v[0:1], v[0:1]
	v_pk_mov_b32 v[22:23], v[0:1], v[0:1]
	v_pk_mov_b32 v[24:25], v[0:1], v[0:1]
	v_pk_mov_b32 v[26:27], v[0:1], v[0:1]
	v_pk_mov_b32 v[28:29], v[0:1], v[0:1]
	v_pk_mov_b32 v[30:31], v[0:1], v[0:1]
	v_pk_mov_b32 v[32:33], v[0:1], v[0:1]
	v_pk_mov_b32 v[34:35], v[0:1], v[0:1]
	v_pk_mov_b32 v[36:37], v[0:1], v[0:1]
	v_pk_mov_b32 v[38:39], v[0:1], v[0:1]
	v_pk_mov_b32 v[40:41], v[0:1], v[0:1]
	v_pk_mov_b32 v[42:43], v[0:1], v[0:1]
	v_pk_mov_b32 v[44:45], v[0:1], v[0:1]
	v_pk_mov_b32 v[46:47], v[0:1], v[0:1]
	v_pk_mov_b32 v[48:49], v[0:1], v[0:1]
	v_pk_mov_b32 v[50:51], v[0:1], v[0:1]
	v_pk_mov_b32 v[52:53], v[0:1], v[0:1]
	v_pk_mov_b32 v[54:55], v[0:1], v[0:1]
	v_pk_mov_b32 v[56:57], v[0:1], v[0:1]
	v_pk_mov_b32 v[58:59], v[0:1], v[0:1]
	v_pk_mov_b32 v[60:61], v[0:1], v[0:1]
	v_pk_mov_b32 v[62:63], v[0:1], v[0:1]
	v_pk_mov_b32 v[64:65], v[0:1], v[0:1]
	v_pk_mov_b32 v[66:67], v[0:1], v[0:1]
	v_pk_mov_b32 v[68:69], v[0:1], v[0:1]
	v_pk_mov_b32 v[70:71], v[0:1], v[0:1]
	v_pk_mov_b32 v[72:73], v[0:1], v[0:1]
	v_pk_mov_b32 v[74:75], v[0:1], v[0:1]
	v_pk_mov_b32 v[76:77], v[0:1], v[0:1]
	v_pk_mov_b32 v[78:79], v[0:1], v[0:1]
	v_pk_mov_b32 v[80:81], v[0:1], v[0:1]
	v_pk_mov_b32 v[82:83], v[0:1], v[0:1]
	v_pk_mov_b32 v[84:85], v[0:1], v[0:1]
	v_pk_mov_b32 v[86:87], v[0:1], v[0:1]
	v_pk_mov_b32 v[88:89], v[0:1], v[0:1]
	v_pk_mov_b32 v[90:91], v[0:1], v[0:1]
	v_pk_mov_b32 v[92:93], v[0:1], v[0:1]
	v_pk_mov_b32 v[94:95], v[0:1], v[0:1]
	v_pk_mov_b32 v[96:97], v[0:1], v[0:1]
	v_pk_mov_b32 v[98:99], v[0:1], v[0:1]
	v_pk_mov_b32 v[100:101], v[0:1], v[0:1]
	v_pk_mov_b32 v[102:103], v[0:1], v[0:1]
	v_pk_mov_b32 v[104:105], v[0:1], v[0:1]
	v_pk_mov_b32 v[106:107], v[0:1], v[0:1]
	v_pk_mov_b32 v[108:109], v[0:1], v[0:1]
	v_pk_mov_b32 v[110:111], v[0:1], v[0:1]
	v_pk_mov_b32 v[112:113], v[0:1], v[0:1]
	v_pk_mov_b32 v[114:115], v[0:1], v[0:1]
	v_pk_mov_b32 v[116:117], v[0:1], v[0:1]
	v_pk_mov_b32 v[118:119], v[0:1], v[0:1]
	v_pk_mov_b32 v[120:121], v[0:1], v[0:1]
	v_pk_mov_b32 v[122:123], v[0:1], v[0:1]
	v_pk_mov_b32 v[124:125], v[0:1], v[0:1]
	v_pk_mov_b32 v[126:127], v[0:1], v[0:1]

; template <class Epi, class Sched, bool ALIGN_EPI = false, bool SP2 = false, bool APERM = false  >
; __device__ __forceinline__ void gemm_phase(PG8_LAS unsigned char* lds, const Gemm g, const Sched& S, const Epi& E, const int wid  ) {
;     ...
;     f32x4 acc[2][2][4][2];
; #pragma unroll
;     for (int a = 0; a < 2; ++a)
; #pragma unroll
;         for (int b = 0; b < 2; ++b)
; #pragma unroll
;             for (int m = 0; m < 4; ++m)
; #pragma unroll
;                 for (int n = 0; n < 2; ++n) acc[a][b][m][n] = (f32x4){0.f, 0.f, 0.f, 0.f};
;     ...
;         for (int a = 0; a < 2; ++a)
; #pragma unroll
;             for (int b = 0; b < 2; ++b)
; #pragma unroll
;                 for (int m = 0; m < 4; ++m)
; #pragma unroll
;                     for (int n = 0; n < 2; ++n) acc[a][b][m][n] = (f32x4){0.f, 0.f, 0.f, 0.f};
.LBB0_693:
	v_mov_b32_e32 v0, 0
	s_mov_b32 s10, s72
	s_mov_b32 s12, s70
	s_mov_b64 s[14:15], s[90:91]
	s_mov_b64 s[0:1], s[88:89]
	s_mov_b32 s84, s96
	v_mov_b32_e32 v1, v0
	v_pk_mov_b32 v[2:3], v[0:1], v[0:1]
	v_pk_mov_b32 v[4:5], v[0:1], v[0:1]
	v_pk_mov_b32 v[6:7], v[0:1], v[0:1]
	v_pk_mov_b32 v[8:9], v[0:1], v[0:1]
	v_pk_mov_b32 v[10:11], v[0:1], v[0:1]
	v_pk_mov_b32 v[12:13], v[0:1], v[0:1]
	v_pk_mov_b32 v[14:15], v[0:1], v[0:1]
	v_pk_mov_b32 v[16:17], v[0:1], v[0:1]
	v_pk_mov_b32 v[18:19], v[0:1], v[0:1]
	v_pk_mov_b32 v[20:21], v[0:1], v[0:1]
	v_pk_mov_b32 v[22:23], v[0:1], v[0:1]
	v_pk_mov_b32 v[24:25], v[0:1], v[0:1]
	v_pk_mov_b32 v[26:27], v[0:1], v[0:1]
	v_pk_mov_b32 v[28:29], v[0:1], v[0:1]
	v_pk_mov_b32 v[30:31], v[0:1], v[0:1]
	v_pk_mov_b32 v[32:33], v[0:1], v[0:1]
	v_pk_mov_b32 v[34:35], v[0:1], v[0:1]
	v_pk_mov_b32 v[36:37], v[0:1], v[0:1]
	v_pk_mov_b32 v[38:39], v[0:1], v[0:1]
	v_pk_mov_b32 v[40:41], v[0:1], v[0:1]
	v_pk_mov_b32 v[42:43], v[0:1], v[0:1]
	v_pk_mov_b32 v[44:45], v[0:1], v[0:1]
	v_pk_mov_b32 v[46:47], v[0:1], v[0:1]
	v_pk_mov_b32 v[48:49], v[0:1], v[0:1]
	v_pk_mov_b32 v[50:51], v[0:1], v[0:1]
	v_pk_mov_b32 v[52:53], v[0:1], v[0:1]
	v_pk_mov_b32 v[54:55], v[0:1], v[0:1]
	v_pk_mov_b32 v[56:57], v[0:1], v[0:1]
	v_pk_mov_b32 v[58:59], v[0:1], v[0:1]
	v_pk_mov_b32 v[60:61], v[0:1], v[0:1]
	v_pk_mov_b32 v[62:63], v[0:1], v[0:1]
	v_pk_mov_b32 v[64:65], v[0:1], v[0:1]
	v_pk_mov_b32 v[66:67], v[0:1], v[0:1]
	v_pk_mov_b32 v[68:69], v[0:1], v[0:1]
	v_pk_mov_b32 v[70:71], v[0:1], v[0:1]
	v_pk_mov_b32 v[72:73], v[0:1], v[0:1]
	v_pk_mov_b32 v[74:75], v[0:1], v[0:1]
	v_pk_mov_b32 v[76:77], v[0:1], v[0:1]
	v_pk_mov_b32 v[78:79], v[0:1], v[0:1]
	v_pk_mov_b32 v[80:81], v[0:1], v[0:1]
	v_pk_mov_b32 v[82:83], v[0:1], v[0:1]
	v_pk_mov_b32 v[84:85], v[0:1], v[0:1]
	v_pk_mov_b32 v[86:87], v[0:1], v[0:1]
	v_pk_mov_b32 v[88:89], v[0:1], v[0:1]
	v_pk_mov_b32 v[90:91], v[0:1], v[0:1]
	v_pk_mov_b32 v[92:93], v[0:1], v[0:1]
	v_pk_mov_b32 v[94:95], v[0:1], v[0:1]
	v_pk_mov_b32 v[96:97], v[0:1], v[0:1]
	v_pk_mov_b32 v[98:99], v[0:1], v[0:1]
	v_pk_mov_b32 v[100:101], v[0:1], v[0:1]
	v_pk_mov_b32 v[102:103], v[0:1], v[0:1]
	v_pk_mov_b32 v[104:105], v[0:1], v[0:1]
	v_pk_mov_b32 v[106:107], v[0:1], v[0:1]
	v_pk_mov_b32 v[108:109], v[0:1], v[0:1]
	v_pk_mov_b32 v[110:111], v[0:1], v[0:1]
	v_pk_mov_b32 v[112:113], v[0:1], v[0:1]
	v_pk_mov_b32 v[114:115], v[0:1], v[0:1]
	v_pk_mov_b32 v[116:117], v[0:1], v[0:1]
	v_pk_mov_b32 v[118:119], v[0:1], v[0:1]
	v_pk_mov_b32 v[120:121], v[0:1], v[0:1]
	v_pk_mov_b32 v[122:123], v[0:1], v[0:1]
	v_pk_mov_b32 v[124:125], v[0:1], v[0:1]
	v_pk_mov_b32 v[126:127], v[0:1], v[0:1]

; template <class Epi, class Sched, bool ALIGN_EPI = false, bool SP2 = false, bool APERM = false  >
; __device__ __forceinline__ void gemm_phase(PG8_LAS unsigned char* lds, const Gemm g, const Sched& S, const Epi& E, const int wid  ) {
;     ...
;     f32x4 acc[2][2][4][2];
; #pragma unroll
;     for (int a = 0; a < 2; ++a)
; #pragma unroll
;         for (int b = 0; b < 2; ++b)
; #pragma unroll
;             for (int m = 0; m < 4; ++m)
; #pragma unroll
;                 for (int n = 0; n < 2; ++n) acc[a][b][m][n] = (f32x4){0.f, 0.f, 0.f, 0.f};
;     ...
;         for (int a = 0; a < 2; ++a)
; #pragma unroll
;             for (int b = 0; b < 2; ++b)
; #pragma unroll
;                 for (int m = 0; m < 4; ++m)
; #pragma unroll
;                     for (int n = 0; n < 2; ++n) acc[a][b][m][n] = (f32x4){0.f, 0.f, 0.f, 0.f};
.LBB0_766:
	v_mov_b32_e32 v0, 0
	s_mov_b32 s14, s88
	s_mov_b32 s54, s86
	s_mov_b64 s[56:57], s[94:95]
	s_mov_b64 s[60:61], s[92:93]
	s_mov_b32 s46, s85
	v_mov_b32_e32 v1, v0
	v_pk_mov_b32 v[2:3], v[0:1], v[0:1]
	v_pk_mov_b32 v[4:5], v[0:1], v[0:1]
	v_pk_mov_b32 v[6:7], v[0:1], v[0:1]
	v_pk_mov_b32 v[8:9], v[0:1], v[0:1]
	v_pk_mov_b32 v[10:11], v[0:1], v[0:1]
	v_pk_mov_b32 v[12:13], v[0:1], v[0:1]
	v_pk_mov_b32 v[14:15], v[0:1], v[0:1]
	v_pk_mov_b32 v[16:17], v[0:1], v[0:1]
	v_pk_mov_b32 v[18:19], v[0:1], v[0:1]
	v_pk_mov_b32 v[20:21], v[0:1], v[0:1]
	v_pk_mov_b32 v[22:23], v[0:1], v[0:1]
	v_pk_mov_b32 v[24:25], v[0:1], v[0:1]
	v_pk_mov_b32 v[26:27], v[0:1], v[0:1]
	v_pk_mov_b32 v[28:29], v[0:1], v[0:1]
	v_pk_mov_b32 v[30:31], v[0:1], v[0:1]
	v_pk_mov_b32 v[32:33], v[0:1], v[0:1]
	v_pk_mov_b32 v[34:35], v[0:1], v[0:1]
	v_pk_mov_b32 v[36:37], v[0:1], v[0:1]
	v_pk_mov_b32 v[38:39], v[0:1], v[0:1]
	v_pk_mov_b32 v[40:41], v[0:1], v[0:1]
	v_pk_mov_b32 v[42:43], v[0:1], v[0:1]
	v_pk_mov_b32 v[44:45], v[0:1], v[0:1]
	v_pk_mov_b32 v[46:47], v[0:1], v[0:1]
	v_pk_mov_b32 v[48:49], v[0:1], v[0:1]
	v_pk_mov_b32 v[50:51], v[0:1], v[0:1]
	v_pk_mov_b32 v[52:53], v[0:1], v[0:1]
	v_pk_mov_b32 v[54:55], v[0:1], v[0:1]
	v_pk_mov_b32 v[56:57], v[0:1], v[0:1]
	v_pk_mov_b32 v[58:59], v[0:1], v[0:1]
	v_pk_mov_b32 v[60:61], v[0:1], v[0:1]
	v_pk_mov_b32 v[62:63], v[0:1], v[0:1]
	v_pk_mov_b32 v[64:65], v[0:1], v[0:1]
	v_pk_mov_b32 v[66:67], v[0:1], v[0:1]
	v_pk_mov_b32 v[68:69], v[0:1], v[0:1]
	v_pk_mov_b32 v[70:71], v[0:1], v[0:1]
	v_pk_mov_b32 v[72:73], v[0:1], v[0:1]
	v_pk_mov_b32 v[74:75], v[0:1], v[0:1]
	v_pk_mov_b32 v[76:77], v[0:1], v[0:1]
	v_pk_mov_b32 v[78:79], v[0:1], v[0:1]
	v_pk_mov_b32 v[80:81], v[0:1], v[0:1]
	v_pk_mov_b32 v[82:83], v[0:1], v[0:1]
	v_pk_mov_b32 v[84:85], v[0:1], v[0:1]
	v_pk_mov_b32 v[86:87], v[0:1], v[0:1]
	v_pk_mov_b32 v[88:89], v[0:1], v[0:1]
	v_pk_mov_b32 v[90:91], v[0:1], v[0:1]
	v_pk_mov_b32 v[92:93], v[0:1], v[0:1]
	v_pk_mov_b32 v[94:95], v[0:1], v[0:1]
	v_pk_mov_b32 v[96:97], v[0:1], v[0:1]
	v_pk_mov_b32 v[98:99], v[0:1], v[0:1]
	v_pk_mov_b32 v[100:101], v[0:1], v[0:1]
	v_pk_mov_b32 v[102:103], v[0:1], v[0:1]
	v_pk_mov_b32 v[104:105], v[0:1], v[0:1]
	v_pk_mov_b32 v[106:107], v[0:1], v[0:1]
	v_pk_mov_b32 v[108:109], v[0:1], v[0:1]
	v_pk_mov_b32 v[110:111], v[0:1], v[0:1]
	v_pk_mov_b32 v[112:113], v[0:1], v[0:1]
	v_pk_mov_b32 v[114:115], v[0:1], v[0:1]
	v_pk_mov_b32 v[116:117], v[0:1], v[0:1]
	v_pk_mov_b32 v[118:119], v[0:1], v[0:1]
	v_pk_mov_b32 v[120:121], v[0:1], v[0:1]
	v_pk_mov_b32 v[122:123], v[0:1], v[0:1]
	v_pk_mov_b32 v[124:125], v[0:1], v[0:1]
	v_pk_mov_b32 v[126:127], v[0:1], v[0:1]

; template <class Epi, class Sched, bool ALIGN_EPI = false, bool SP2 = false, bool APERM = false  >
; __device__ __forceinline__ void gemm_phase(PG8_LAS unsigned char* lds, const Gemm g, const Sched& S, const Epi& E, const int wid  ) {
;     ...
;     f32x4 acc[2][2][4][2];
; #pragma unroll
;     for (int a = 0; a < 2; ++a)
; #pragma unroll
;         for (int b = 0; b < 2; ++b)
; #pragma unroll
;             for (int m = 0; m < 4; ++m)
; #pragma unroll
;                 for (int n = 0; n < 2; ++n) acc[a][b][m][n] = (f32x4){0.f, 0.f, 0.f, 0.f};
;     ...
;         for (int a = 0; a < 2; ++a)
; #pragma unroll
;             for (int b = 0; b < 2; ++b)
; #pragma unroll
;                 for (int m = 0; m < 4; ++m)
; #pragma unroll
;                     for (int n = 0; n < 2; ++n) acc[a][b][m][n] = (f32x4){0.f, 0.f, 0.f, 0.f};
.LBB0_1015:
	v_mov_b32_e32 v0, 0
	s_mov_b32 s6, s72
	s_mov_b32 s8, s28
	v_mov_b32_e32 v1, v0
	v_pk_mov_b32 v[2:3], v[0:1], v[0:1]
	v_pk_mov_b32 v[4:5], v[0:1], v[0:1]
	v_pk_mov_b32 v[6:7], v[0:1], v[0:1]
	v_pk_mov_b32 v[8:9], v[0:1], v[0:1]
	v_pk_mov_b32 v[10:11], v[0:1], v[0:1]
	v_pk_mov_b32 v[12:13], v[0:1], v[0:1]
	v_pk_mov_b32 v[14:15], v[0:1], v[0:1]
	v_pk_mov_b32 v[16:17], v[0:1], v[0:1]
	v_pk_mov_b32 v[18:19], v[0:1], v[0:1]
	v_pk_mov_b32 v[20:21], v[0:1], v[0:1]
	v_pk_mov_b32 v[22:23], v[0:1], v[0:1]
	v_pk_mov_b32 v[24:25], v[0:1], v[0:1]
	v_pk_mov_b32 v[26:27], v[0:1], v[0:1]
	v_pk_mov_b32 v[28:29], v[0:1], v[0:1]
	v_pk_mov_b32 v[30:31], v[0:1], v[0:1]
	v_pk_mov_b32 v[32:33], v[0:1], v[0:1]
	v_pk_mov_b32 v[34:35], v[0:1], v[0:1]
	v_pk_mov_b32 v[36:37], v[0:1], v[0:1]
	v_pk_mov_b32 v[38:39], v[0:1], v[0:1]
	v_pk_mov_b32 v[40:41], v[0:1], v[0:1]
	v_pk_mov_b32 v[42:43], v[0:1], v[0:1]
	v_pk_mov_b32 v[44:45], v[0:1], v[0:1]
	v_pk_mov_b32 v[46:47], v[0:1], v[0:1]
	v_pk_mov_b32 v[48:49], v[0:1], v[0:1]
	v_pk_mov_b32 v[50:51], v[0:1], v[0:1]
	v_pk_mov_b32 v[52:53], v[0:1], v[0:1]
	v_pk_mov_b32 v[54:55], v[0:1], v[0:1]
	v_pk_mov_b32 v[56:57], v[0:1], v[0:1]
	v_pk_mov_b32 v[58:59], v[0:1], v[0:1]
	v_pk_mov_b32 v[60:61], v[0:1], v[0:1]
	v_pk_mov_b32 v[62:63], v[0:1], v[0:1]
	v_pk_mov_b32 v[64:65], v[0:1], v[0:1]
	v_pk_mov_b32 v[66:67], v[0:1], v[0:1]
	v_pk_mov_b32 v[68:69], v[0:1], v[0:1]
	v_pk_mov_b32 v[70:71], v[0:1], v[0:1]
	v_pk_mov_b32 v[72:73], v[0:1], v[0:1]
	v_pk_mov_b32 v[74:75], v[0:1], v[0:1]
	v_pk_mov_b32 v[76:77], v[0:1], v[0:1]
	v_pk_mov_b32 v[78:79], v[0:1], v[0:1]
	v_pk_mov_b32 v[80:81], v[0:1], v[0:1]
	v_pk_mov_b32 v[82:83], v[0:1], v[0:1]
	v_pk_mov_b32 v[84:85], v[0:1], v[0:1]
	v_pk_mov_b32 v[86:87], v[0:1], v[0:1]
	v_pk_mov_b32 v[88:89], v[0:1], v[0:1]
	v_pk_mov_b32 v[90:91], v[0:1], v[0:1]
	v_pk_mov_b32 v[92:93], v[0:1], v[0:1]
	v_pk_mov_b32 v[94:95], v[0:1], v[0:1]
	v_pk_mov_b32 v[96:97], v[0:1], v[0:1]
	v_pk_mov_b32 v[98:99], v[0:1], v[0:1]
	v_pk_mov_b32 v[100:101], v[0:1], v[0:1]
	v_pk_mov_b32 v[102:103], v[0:1], v[0:1]
	v_pk_mov_b32 v[104:105], v[0:1], v[0:1]
	v_pk_mov_b32 v[106:107], v[0:1], v[0:1]
	v_pk_mov_b32 v[108:109], v[0:1], v[0:1]
	v_pk_mov_b32 v[110:111], v[0:1], v[0:1]
	v_pk_mov_b32 v[112:113], v[0:1], v[0:1]
	v_pk_mov_b32 v[114:115], v[0:1], v[0:1]
	v_pk_mov_b32 v[116:117], v[0:1], v[0:1]
	v_pk_mov_b32 v[118:119], v[0:1], v[0:1]
	v_pk_mov_b32 v[120:121], v[0:1], v[0:1]
	v_pk_mov_b32 v[122:123], v[0:1], v[0:1]
	v_pk_mov_b32 v[124:125], v[0:1], v[0:1]
	v_pk_mov_b32 v[126:127], v[0:1], v[0:1]
	s_mov_b64 s[34:35], s[26:27]
	s_mov_b32 s94, s95
	s_andn2_b64 vcc, exec, s[30:31]
	s_mov_b64 s[78:79], s[74:75]
	s_cbranch_vccz .LBB0_1049

; template <class Epi, class Sched, bool ALIGN_EPI = false, bool SP2 = false, bool APERM = false  >
; __device__ __forceinline__ void gemm_phase(PG8_LAS unsigned char* lds, const Gemm g, const Sched& S, const Epi& E, const int wid  ) {
;     ...
;     f32x4 acc[2][2][4][2];
; #pragma unroll
;     for (int a = 0; a < 2; ++a)
; #pragma unroll
;         for (int b = 0; b < 2; ++b)
; #pragma unroll
;             for (int m = 0; m < 4; ++m)
; #pragma unroll
;                 for (int n = 0; n < 2; ++n) acc[a][b][m][n] = (f32x4){0.f, 0.f, 0.f, 0.f};
;     ...
;         for (int a = 0; a < 2; ++a)
; #pragma unroll
;             for (int b = 0; b < 2; ++b)
; #pragma unroll
;                 for (int m = 0; m < 4; ++m)
; #pragma unroll
;                     for (int n = 0; n < 2; ++n) acc[a][b][m][n] = (f32x4){0.f, 0.f, 0.f, 0.f};
.LBB0_1173:
	v_mov_b32_e32 v0, 0
	s_mov_b32 s34, s82
	s_mov_b32 s8, s80
	s_mov_b64 s[36:37], s[28:29]
	s_mov_b64 s[44:45], s[24:25]
	s_mov_b32 s5, s4
	v_mov_b32_e32 v1, v0
	v_pk_mov_b32 v[2:3], v[0:1], v[0:1]
	v_pk_mov_b32 v[4:5], v[0:1], v[0:1]
	v_pk_mov_b32 v[6:7], v[0:1], v[0:1]
	v_pk_mov_b32 v[8:9], v[0:1], v[0:1]
	v_pk_mov_b32 v[10:11], v[0:1], v[0:1]
	v_pk_mov_b32 v[12:13], v[0:1], v[0:1]
	v_pk_mov_b32 v[14:15], v[0:1], v[0:1]
	v_pk_mov_b32 v[16:17], v[0:1], v[0:1]
	v_pk_mov_b32 v[18:19], v[0:1], v[0:1]
	v_pk_mov_b32 v[20:21], v[0:1], v[0:1]
	v_pk_mov_b32 v[22:23], v[0:1], v[0:1]
	v_pk_mov_b32 v[24:25], v[0:1], v[0:1]
	v_pk_mov_b32 v[26:27], v[0:1], v[0:1]
	v_pk_mov_b32 v[28:29], v[0:1], v[0:1]
	v_pk_mov_b32 v[30:31], v[0:1], v[0:1]
	v_pk_mov_b32 v[32:33], v[0:1], v[0:1]
	v_pk_mov_b32 v[34:35], v[0:1], v[0:1]
	v_pk_mov_b32 v[36:37], v[0:1], v[0:1]
	v_pk_mov_b32 v[38:39], v[0:1], v[0:1]
	v_pk_mov_b32 v[40:41], v[0:1], v[0:1]
	v_pk_mov_b32 v[42:43], v[0:1], v[0:1]
	v_pk_mov_b32 v[44:45], v[0:1], v[0:1]
	v_pk_mov_b32 v[46:47], v[0:1], v[0:1]
	v_pk_mov_b32 v[48:49], v[0:1], v[0:1]
	v_pk_mov_b32 v[50:51], v[0:1], v[0:1]
	v_pk_mov_b32 v[52:53], v[0:1], v[0:1]
	v_pk_mov_b32 v[54:55], v[0:1], v[0:1]
	v_pk_mov_b32 v[56:57], v[0:1], v[0:1]
	v_pk_mov_b32 v[58:59], v[0:1], v[0:1]
	v_pk_mov_b32 v[60:61], v[0:1], v[0:1]
	v_pk_mov_b32 v[62:63], v[0:1], v[0:1]
	v_pk_mov_b32 v[64:65], v[0:1], v[0:1]
	v_pk_mov_b32 v[66:67], v[0:1], v[0:1]
	v_pk_mov_b32 v[68:69], v[0:1], v[0:1]
	v_pk_mov_b32 v[70:71], v[0:1], v[0:1]
	v_pk_mov_b32 v[72:73], v[0:1], v[0:1]
	v_pk_mov_b32 v[74:75], v[0:1], v[0:1]
	v_pk_mov_b32 v[76:77], v[0:1], v[0:1]
	v_pk_mov_b32 v[78:79], v[0:1], v[0:1]
	v_pk_mov_b32 v[80:81], v[0:1], v[0:1]
	v_pk_mov_b32 v[82:83], v[0:1], v[0:1]
	v_pk_mov_b32 v[84:85], v[0:1], v[0:1]
	v_pk_mov_b32 v[86:87], v[0:1], v[0:1]
	v_pk_mov_b32 v[88:89], v[0:1], v[0:1]
	v_pk_mov_b32 v[90:91], v[0:1], v[0:1]
	v_pk_mov_b32 v[92:93], v[0:1], v[0:1]
	v_pk_mov_b32 v[94:95], v[0:1], v[0:1]
	v_pk_mov_b32 v[96:97], v[0:1], v[0:1]
	v_pk_mov_b32 v[98:99], v[0:1], v[0:1]
	v_pk_mov_b32 v[100:101], v[0:1], v[0:1]
	v_pk_mov_b32 v[102:103], v[0:1], v[0:1]
	v_pk_mov_b32 v[104:105], v[0:1], v[0:1]
	v_pk_mov_b32 v[106:107], v[0:1], v[0:1]
	v_pk_mov_b32 v[108:109], v[0:1], v[0:1]
	v_pk_mov_b32 v[110:111], v[0:1], v[0:1]
	v_pk_mov_b32 v[112:113], v[0:1], v[0:1]
	v_pk_mov_b32 v[114:115], v[0:1], v[0:1]
	v_pk_mov_b32 v[116:117], v[0:1], v[0:1]
	v_pk_mov_b32 v[118:119], v[0:1], v[0:1]
	v_pk_mov_b32 v[120:121], v[0:1], v[0:1]
	v_pk_mov_b32 v[122:123], v[0:1], v[0:1]
	v_pk_mov_b32 v[124:125], v[0:1], v[0:1]
	v_pk_mov_b32 v[126:127], v[0:1], v[0:1]

; template <class Epi, class Sched, bool ALIGN_EPI = false, bool SP2 = false, bool APERM = false  >
; __device__ __forceinline__ void gemm_phase(PG8_LAS unsigned char* lds, const Gemm g, const Sched& S, const Epi& E, const int wid  ) {
;     ...
;     f32x4 acc[2][2][4][2];
; #pragma unroll
;     for (int a = 0; a < 2; ++a)
; #pragma unroll
;         for (int b = 0; b < 2; ++b)
; #pragma unroll
;             for (int m = 0; m < 4; ++m)
; #pragma unroll
;                 for (int n = 0; n < 2; ++n) acc[a][b][m][n] = (f32x4){0.f, 0.f, 0.f, 0.f};
;     ...
;         for (int a = 0; a < 2; ++a)
; #pragma unroll
;             for (int b = 0; b < 2; ++b)
; #pragma unroll
;                 for (int m = 0; m < 4; ++m)
; #pragma unroll
;                     for (int n = 0; n < 2; ++n) acc[a][b][m][n] = (f32x4){0.f, 0.f, 0.f, 0.f};
.LBB0_1226:
	v_mov_b32_e32 v0, 0
	s_mov_b32 s83, s97
	s_mov_b32 s76, s84
	s_mov_b64 s[10:11], s[66:67]
	s_mov_b64 s[14:15], s[64:65]
	s_mov_b32 s77, s94
	v_mov_b32_e32 v1, v0
	v_pk_mov_b32 v[2:3], v[0:1], v[0:1]
	v_pk_mov_b32 v[4:5], v[0:1], v[0:1]
	v_pk_mov_b32 v[6:7], v[0:1], v[0:1]
	v_pk_mov_b32 v[8:9], v[0:1], v[0:1]
	v_pk_mov_b32 v[10:11], v[0:1], v[0:1]
	v_pk_mov_b32 v[12:13], v[0:1], v[0:1]
	v_pk_mov_b32 v[14:15], v[0:1], v[0:1]
	v_pk_mov_b32 v[16:17], v[0:1], v[0:1]
	v_pk_mov_b32 v[18:19], v[0:1], v[0:1]
	v_pk_mov_b32 v[20:21], v[0:1], v[0:1]
	v_pk_mov_b32 v[22:23], v[0:1], v[0:1]
	v_pk_mov_b32 v[24:25], v[0:1], v[0:1]
	v_pk_mov_b32 v[26:27], v[0:1], v[0:1]
	v_pk_mov_b32 v[28:29], v[0:1], v[0:1]
	v_pk_mov_b32 v[30:31], v[0:1], v[0:1]
	v_pk_mov_b32 v[32:33], v[0:1], v[0:1]
	v_pk_mov_b32 v[34:35], v[0:1], v[0:1]
	v_pk_mov_b32 v[36:37], v[0:1], v[0:1]
	v_pk_mov_b32 v[38:39], v[0:1], v[0:1]
	v_pk_mov_b32 v[40:41], v[0:1], v[0:1]
	v_pk_mov_b32 v[42:43], v[0:1], v[0:1]
	v_pk_mov_b32 v[44:45], v[0:1], v[0:1]
	v_pk_mov_b32 v[46:47], v[0:1], v[0:1]
	v_pk_mov_b32 v[48:49], v[0:1], v[0:1]
	v_pk_mov_b32 v[50:51], v[0:1], v[0:1]
	v_pk_mov_b32 v[52:53], v[0:1], v[0:1]
	v_pk_mov_b32 v[54:55], v[0:1], v[0:1]
	v_pk_mov_b32 v[56:57], v[0:1], v[0:1]
	v_pk_mov_b32 v[58:59], v[0:1], v[0:1]
	v_pk_mov_b32 v[60:61], v[0:1], v[0:1]
	v_pk_mov_b32 v[62:63], v[0:1], v[0:1]
	v_pk_mov_b32 v[64:65], v[0:1], v[0:1]
	v_pk_mov_b32 v[66:67], v[0:1], v[0:1]
	v_pk_mov_b32 v[68:69], v[0:1], v[0:1]
	v_pk_mov_b32 v[70:71], v[0:1], v[0:1]
	v_pk_mov_b32 v[72:73], v[0:1], v[0:1]
	v_pk_mov_b32 v[74:75], v[0:1], v[0:1]
	v_pk_mov_b32 v[76:77], v[0:1], v[0:1]
	v_pk_mov_b32 v[78:79], v[0:1], v[0:1]
	v_pk_mov_b32 v[80:81], v[0:1], v[0:1]
	v_pk_mov_b32 v[82:83], v[0:1], v[0:1]
	v_pk_mov_b32 v[84:85], v[0:1], v[0:1]
	v_pk_mov_b32 v[86:87], v[0:1], v[0:1]
	v_pk_mov_b32 v[88:89], v[0:1], v[0:1]
	v_pk_mov_b32 v[90:91], v[0:1], v[0:1]
	v_pk_mov_b32 v[92:93], v[0:1], v[0:1]
	v_pk_mov_b32 v[94:95], v[0:1], v[0:1]
	v_pk_mov_b32 v[96:97], v[0:1], v[0:1]
	v_pk_mov_b32 v[98:99], v[0:1], v[0:1]
	v_pk_mov_b32 v[100:101], v[0:1], v[0:1]
	v_pk_mov_b32 v[102:103], v[0:1], v[0:1]
	v_pk_mov_b32 v[104:105], v[0:1], v[0:1]
	v_pk_mov_b32 v[106:107], v[0:1], v[0:1]
	v_pk_mov_b32 v[108:109], v[0:1], v[0:1]
	v_pk_mov_b32 v[110:111], v[0:1], v[0:1]
	v_pk_mov_b32 v[112:113], v[0:1], v[0:1]
	v_pk_mov_b32 v[114:115], v[0:1], v[0:1]
	v_pk_mov_b32 v[116:117], v[0:1], v[0:1]
	v_pk_mov_b32 v[118:119], v[0:1], v[0:1]
	v_pk_mov_b32 v[120:121], v[0:1], v[0:1]
	v_pk_mov_b32 v[122:123], v[0:1], v[0:1]
	v_pk_mov_b32 v[124:125], v[0:1], v[0:1]
	v_pk_mov_b32 v[126:127], v[0:1], v[0:1]

; template <class Epi, class Sched, bool ALIGN_EPI = false, bool SP2 = false, bool APERM = false  >
; __device__ __forceinline__ void gemm_phase(PG8_LAS unsigned char* lds, const Gemm g, const Sched& S, const Epi& E, const int wid  ) {
;     ...
;     f32x4 acc[2][2][4][2];
; #pragma unroll
;     for (int a = 0; a < 2; ++a)
; #pragma unroll
;         for (int b = 0; b < 2; ++b)
; #pragma unroll
;             for (int m = 0; m < 4; ++m)
; #pragma unroll
;                 for (int n = 0; n < 2; ++n) acc[a][b][m][n] = (f32x4){0.f, 0.f, 0.f, 0.f};
;     ...
;         for (int a = 0; a < 2; ++a)
; #pragma unroll
;             for (int b = 0; b < 2; ++b)
; #pragma unroll
;                 for (int m = 0; m < 4; ++m)
; #pragma unroll
;                     for (int n = 0; n < 2; ++n) acc[a][b][m][n] = (f32x4){0.f, 0.f, 0.f, 0.f};
.LBB0_1288:
	v_mov_b32_e32 v0, 0
	s_mov_b32 s81, s96
	s_mov_b32 s82, s97
	s_mov_b64 s[10:11], s[28:29]
	s_mov_b64 s[14:15], s[24:25]
	s_mov_b32 s92, s91
	v_mov_b32_e32 v1, v0
	v_pk_mov_b32 v[2:3], v[0:1], v[0:1]
	v_pk_mov_b32 v[4:5], v[0:1], v[0:1]
	v_pk_mov_b32 v[6:7], v[0:1], v[0:1]
	v_pk_mov_b32 v[8:9], v[0:1], v[0:1]
	v_pk_mov_b32 v[10:11], v[0:1], v[0:1]
	v_pk_mov_b32 v[12:13], v[0:1], v[0:1]
	v_pk_mov_b32 v[14:15], v[0:1], v[0:1]
	v_pk_mov_b32 v[16:17], v[0:1], v[0:1]
	v_pk_mov_b32 v[18:19], v[0:1], v[0:1]
	v_pk_mov_b32 v[20:21], v[0:1], v[0:1]
	v_pk_mov_b32 v[22:23], v[0:1], v[0:1]
	v_pk_mov_b32 v[24:25], v[0:1], v[0:1]
	v_pk_mov_b32 v[26:27], v[0:1], v[0:1]
	v_pk_mov_b32 v[28:29], v[0:1], v[0:1]
	v_pk_mov_b32 v[30:31], v[0:1], v[0:1]
	v_pk_mov_b32 v[32:33], v[0:1], v[0:1]
	v_pk_mov_b32 v[34:35], v[0:1], v[0:1]
	v_pk_mov_b32 v[36:37], v[0:1], v[0:1]
	v_pk_mov_b32 v[38:39], v[0:1], v[0:1]
	v_pk_mov_b32 v[40:41], v[0:1], v[0:1]
	v_pk_mov_b32 v[42:43], v[0:1], v[0:1]
	v_pk_mov_b32 v[44:45], v[0:1], v[0:1]
	v_pk_mov_b32 v[46:47], v[0:1], v[0:1]
	v_pk_mov_b32 v[48:49], v[0:1], v[0:1]
	v_pk_mov_b32 v[50:51], v[0:1], v[0:1]
	v_pk_mov_b32 v[52:53], v[0:1], v[0:1]
	v_pk_mov_b32 v[54:55], v[0:1], v[0:1]
	v_pk_mov_b32 v[56:57], v[0:1], v[0:1]
	v_pk_mov_b32 v[58:59], v[0:1], v[0:1]
	v_pk_mov_b32 v[60:61], v[0:1], v[0:1]
	v_pk_mov_b32 v[62:63], v[0:1], v[0:1]
	v_pk_mov_b32 v[64:65], v[0:1], v[0:1]
	v_pk_mov_b32 v[66:67], v[0:1], v[0:1]
	v_pk_mov_b32 v[68:69], v[0:1], v[0:1]
	v_pk_mov_b32 v[70:71], v[0:1], v[0:1]
	v_pk_mov_b32 v[72:73], v[0:1], v[0:1]
	v_pk_mov_b32 v[74:75], v[0:1], v[0:1]
	v_pk_mov_b32 v[76:77], v[0:1], v[0:1]
	v_pk_mov_b32 v[78:79], v[0:1], v[0:1]
	v_pk_mov_b32 v[80:81], v[0:1], v[0:1]
	v_pk_mov_b32 v[82:83], v[0:1], v[0:1]
	v_pk_mov_b32 v[84:85], v[0:1], v[0:1]
	v_pk_mov_b32 v[86:87], v[0:1], v[0:1]
	v_pk_mov_b32 v[88:89], v[0:1], v[0:1]
	v_pk_mov_b32 v[90:91], v[0:1], v[0:1]
	v_pk_mov_b32 v[92:93], v[0:1], v[0:1]
	v_pk_mov_b32 v[94:95], v[0:1], v[0:1]
	v_pk_mov_b32 v[96:97], v[0:1], v[0:1]
	v_pk_mov_b32 v[98:99], v[0:1], v[0:1]
	v_pk_mov_b32 v[100:101], v[0:1], v[0:1]
	v_pk_mov_b32 v[102:103], v[0:1], v[0:1]
	v_pk_mov_b32 v[104:105], v[0:1], v[0:1]
	v_pk_mov_b32 v[106:107], v[0:1], v[0:1]
	v_pk_mov_b32 v[108:109], v[0:1], v[0:1]
	v_pk_mov_b32 v[110:111], v[0:1], v[0:1]
	v_pk_mov_b32 v[112:113], v[0:1], v[0:1]
	v_pk_mov_b32 v[114:115], v[0:1], v[0:1]
	v_pk_mov_b32 v[116:117], v[0:1], v[0:1]
	v_pk_mov_b32 v[118:119], v[0:1], v[0:1]
	v_pk_mov_b32 v[120:121], v[0:1], v[0:1]
	v_pk_mov_b32 v[122:123], v[0:1], v[0:1]
	v_pk_mov_b32 v[124:125], v[0:1], v[0:1]
	v_pk_mov_b32 v[126:127], v[0:1], v[0:1]

; template <class Epi, class Sched, bool ALIGN_EPI = false, bool SP2 = false, bool APERM = false  >
; __device__ __forceinline__ void gemm_phase(PG8_LAS unsigned char* lds, const Gemm g, const Sched& S, const Epi& E, const int wid  ) {
;     ...
;     f32x4 acc[2][2][4][2];
; #pragma unroll
;     for (int a = 0; a < 2; ++a)
; #pragma unroll
;         for (int b = 0; b < 2; ++b)
; #pragma unroll
;             for (int m = 0; m < 4; ++m)
; #pragma unroll
;                 for (int n = 0; n < 2; ++n) acc[a][b][m][n] = (f32x4){0.f, 0.f, 0.f, 0.f};
;     ...
;         for (int a = 0; a < 2; ++a)
; #pragma unroll
;             for (int b = 0; b < 2; ++b)
; #pragma unroll
;                 for (int m = 0; m < 4; ++m)
; #pragma unroll
;                     for (int n = 0; n < 2; ++n) acc[a][b][m][n] = (f32x4){0.f, 0.f, 0.f, 0.f};
.LBB0_1401:
	v_mov_b32_e32 v0, 0
	s_mov_b32 s10, s66
	s_mov_b32 s12, s64
	s_mov_b64 s[14:15], s[72:73]
	s_mov_b64 s[30:31], s[70:71]
	s_mov_b32 s83, s87
	v_mov_b32_e32 v1, v0
	v_pk_mov_b32 v[2:3], v[0:1], v[0:1]
	v_pk_mov_b32 v[4:5], v[0:1], v[0:1]
	v_pk_mov_b32 v[6:7], v[0:1], v[0:1]
	v_pk_mov_b32 v[8:9], v[0:1], v[0:1]
	v_pk_mov_b32 v[10:11], v[0:1], v[0:1]
	v_pk_mov_b32 v[12:13], v[0:1], v[0:1]
	v_pk_mov_b32 v[14:15], v[0:1], v[0:1]
	v_pk_mov_b32 v[16:17], v[0:1], v[0:1]
	v_pk_mov_b32 v[18:19], v[0:1], v[0:1]
	v_pk_mov_b32 v[20:21], v[0:1], v[0:1]
	v_pk_mov_b32 v[22:23], v[0:1], v[0:1]
	v_pk_mov_b32 v[24:25], v[0:1], v[0:1]
	v_pk_mov_b32 v[26:27], v[0:1], v[0:1]
	v_pk_mov_b32 v[28:29], v[0:1], v[0:1]
	v_pk_mov_b32 v[30:31], v[0:1], v[0:1]
	v_pk_mov_b32 v[32:33], v[0:1], v[0:1]
	v_pk_mov_b32 v[34:35], v[0:1], v[0:1]
	v_pk_mov_b32 v[36:37], v[0:1], v[0:1]
	v_pk_mov_b32 v[38:39], v[0:1], v[0:1]
	v_pk_mov_b32 v[40:41], v[0:1], v[0:1]
	v_pk_mov_b32 v[42:43], v[0:1], v[0:1]
	v_pk_mov_b32 v[44:45], v[0:1], v[0:1]
	v_pk_mov_b32 v[46:47], v[0:1], v[0:1]
	v_pk_mov_b32 v[48:49], v[0:1], v[0:1]
	v_pk_mov_b32 v[50:51], v[0:1], v[0:1]
	v_pk_mov_b32 v[52:53], v[0:1], v[0:1]
	v_pk_mov_b32 v[54:55], v[0:1], v[0:1]
	v_pk_mov_b32 v[56:57], v[0:1], v[0:1]
	v_pk_mov_b32 v[58:59], v[0:1], v[0:1]
	v_pk_mov_b32 v[60:61], v[0:1], v[0:1]
	v_pk_mov_b32 v[62:63], v[0:1], v[0:1]
	v_pk_mov_b32 v[64:65], v[0:1], v[0:1]
	v_pk_mov_b32 v[66:67], v[0:1], v[0:1]
	v_pk_mov_b32 v[68:69], v[0:1], v[0:1]
	v_pk_mov_b32 v[70:71], v[0:1], v[0:1]
	v_pk_mov_b32 v[72:73], v[0:1], v[0:1]
	v_pk_mov_b32 v[74:75], v[0:1], v[0:1]
	v_pk_mov_b32 v[76:77], v[0:1], v[0:1]
	v_pk_mov_b32 v[78:79], v[0:1], v[0:1]
	v_pk_mov_b32 v[80:81], v[0:1], v[0:1]
	v_pk_mov_b32 v[82:83], v[0:1], v[0:1]
	v_pk_mov_b32 v[84:85], v[0:1], v[0:1]
	v_pk_mov_b32 v[86:87], v[0:1], v[0:1]
	v_pk_mov_b32 v[88:89], v[0:1], v[0:1]
	v_pk_mov_b32 v[90:91], v[0:1], v[0:1]
	v_pk_mov_b32 v[92:93], v[0:1], v[0:1]
	v_pk_mov_b32 v[94:95], v[0:1], v[0:1]
	v_pk_mov_b32 v[96:97], v[0:1], v[0:1]
	v_pk_mov_b32 v[98:99], v[0:1], v[0:1]
	v_pk_mov_b32 v[100:101], v[0:1], v[0:1]
	v_pk_mov_b32 v[102:103], v[0:1], v[0:1]
	v_pk_mov_b32 v[104:105], v[0:1], v[0:1]
	v_pk_mov_b32 v[106:107], v[0:1], v[0:1]
	v_pk_mov_b32 v[108:109], v[0:1], v[0:1]
	v_pk_mov_b32 v[110:111], v[0:1], v[0:1]
	v_pk_mov_b32 v[112:113], v[0:1], v[0:1]
	v_pk_mov_b32 v[114:115], v[0:1], v[0:1]
	v_pk_mov_b32 v[116:117], v[0:1], v[0:1]
	v_pk_mov_b32 v[118:119], v[0:1], v[0:1]
	v_pk_mov_b32 v[120:121], v[0:1], v[0:1]
	v_pk_mov_b32 v[122:123], v[0:1], v[0:1]
	v_pk_mov_b32 v[124:125], v[0:1], v[0:1]
	v_pk_mov_b32 v[126:127], v[0:1], v[0:1]
